# attention work queue: next-unit ticket taken in the unit epilogue instead of at the unit start (no one-ahead reservation), plus the earlier prologue load batching
# speedup vs baseline: 1.0202x; 1.0202x over previous
.LBB0_128:
	s_or_b64 exec, exec, s[4:5]
	s_cmp_lg_u32 s13, 0
	s_cbranch_scc1 .Ltk_skip0
	s_mov_b64 s[4:5], exec
	s_mov_b64 exec, 1
	v_mov_b32_e32 v96, 1
	global_atomic_add v96, v193, v96, s[8:9] sc0
	s_mov_b64 exec, s[4:5]
.Ltk_skip0:
	s_waitcnt lgkmcnt(0)
	ds_read_b128 v[32:35], v216 offset:49280
	ds_read_b128 v[36:39], v216 offset:49312
	s_lshl_b64 s[2:3], s[2:3], 12
	v_readlane_b32 s4, v252, 37
	s_add_u32 s5, s4, s2
	s_waitcnt lgkmcnt(1)
	v_rcp_f32_e32 v40, v32
	v_readlane_b32 s2, v252, 38
	s_addc_u32 s6, s2, s3
	s_lshl_b64 s[2:3], s[14:15], 1
	v_readlane_b32 s4, v252, 35
	v_rcp_f32_e32 v41, v33
	s_add_u32 s7, s4, s2
	v_readlane_b32 s2, v252, 36
	s_addc_u32 s14, s2, s3
	s_lshl_b32 s2, s13, 12
	s_add_i32 s4, s2, 0
	v_lshlrev_b32_e32 v48, 1, v211
	v_lshlrev_b32_e32 v49, 9, v212
	v_mul_f32_e32 v0, v0, v40
	v_add3_u32 v48, s4, v48, v49
	v_cvt_pk_bf16_f32 v0, v0, s0
	v_rcp_f32_e32 v42, v34
	v_rcp_f32_e32 v43, v35
	s_waitcnt lgkmcnt(0)
	v_rcp_f32_e32 v44, v36
	ds_read_b128 v[32:35], v216 offset:49344
	v_rcp_f32_e32 v45, v37
	v_rcp_f32_e32 v46, v38
	v_rcp_f32_e32 v47, v39
	ds_read_b128 v[36:39], v216 offset:49376
	ds_write_b16 v48, v0 offset:51264
	v_mul_f32_e32 v0, v17, v41
	v_cvt_pk_bf16_f32 v0, v0, s0
	ds_write_b16 v48, v0 offset:51328
	v_mul_f32_e32 v0, v1, v41
	v_cvt_pk_bf16_f32 v0, v0, s0
	ds_write_b16 v48, v0 offset:51392
	v_mul_f32_e32 v0, v18, v42
	v_cvt_pk_bf16_f32 v0, v0, s0
	ds_write_b16 v48, v0 offset:51456
	v_mul_f32_e32 v0, v2, v42
	v_cvt_pk_bf16_f32 v0, v0, s0
	ds_write_b16 v48, v0 offset:51520
	v_mul_f32_e32 v0, v19, v43
	v_cvt_pk_bf16_f32 v0, v0, s0
	ds_write_b16 v48, v0 offset:51584
	v_mul_f32_e32 v0, v3, v43
	v_cvt_pk_bf16_f32 v0, v0, s0
	ds_write_b16 v48, v0 offset:51648
	v_mul_f32_e32 v0, v20, v44
	v_cvt_pk_bf16_f32 v0, v0, s0
	ds_write_b16 v48, v0 offset:52224
	v_mul_f32_e32 v0, v4, v44
	v_cvt_pk_bf16_f32 v0, v0, s0
	ds_write_b16 v48, v0 offset:52288
	v_mul_f32_e32 v0, v21, v45
	v_cvt_pk_bf16_f32 v0, v0, s0
	ds_write_b16 v48, v0 offset:52352
	v_mul_f32_e32 v0, v5, v45
	v_cvt_pk_bf16_f32 v0, v0, s0
	ds_write_b16 v48, v0 offset:52416
	v_mul_f32_e32 v0, v22, v46
	v_cvt_pk_bf16_f32 v0, v0, s0
	ds_write_b16 v48, v0 offset:52480
	v_mul_f32_e32 v0, v6, v46
	v_cvt_pk_bf16_f32 v0, v0, s0
	s_waitcnt lgkmcnt(13)
	v_rcp_f32_e32 v32, v32
	ds_write_b16 v48, v0 offset:52544
	v_mul_f32_e32 v0, v23, v47
	v_cvt_pk_bf16_f32 v0, v0, s0
	ds_write_b16 v48, v0 offset:52608
	v_mul_f32_e32 v0, v7, v47
	v_cvt_pk_bf16_f32 v0, v0, s0
	v_rcp_f32_e32 v33, v33
	ds_write_b16 v48, v0 offset:52672
	v_mul_f32_e32 v0, v24, v32
	v_cvt_pk_bf16_f32 v0, v0, s0
	ds_write_b16 v48, v0 offset:53248
	v_mul_f32_e32 v0, v8, v32
	v_cvt_pk_bf16_f32 v0, v0, s0
	v_rcp_f32_e32 v34, v34
	ds_write_b16 v48, v0 offset:53312
	v_mul_f32_e32 v0, v25, v33
	v_cvt_pk_bf16_f32 v0, v0, s0
	ds_write_b16 v48, v0 offset:53376
	v_mul_f32_e32 v0, v9, v33
	v_cvt_pk_bf16_f32 v0, v0, s0
	v_rcp_f32_e32 v35, v35
	ds_write_b16 v48, v0 offset:53440
	v_mul_f32_e32 v0, v26, v34
	v_cvt_pk_bf16_f32 v0, v0, s0
	ds_write_b16 v48, v0 offset:53504
	v_mul_f32_e32 v0, v10, v34
	v_cvt_pk_bf16_f32 v0, v0, s0
	s_waitcnt lgkmcnt(14)
	v_rcp_f32_e32 v36, v36
	ds_write_b16 v48, v0 offset:53568
	v_mul_f32_e32 v0, v27, v35
	v_cvt_pk_bf16_f32 v0, v0, s0
	ds_write_b16 v48, v0 offset:53632
	v_mul_f32_e32 v0, v11, v35
	v_cvt_pk_bf16_f32 v0, v0, s0
	v_rcp_f32_e32 v37, v37
	ds_write_b16 v48, v0 offset:53696
	v_mul_f32_e32 v0, v28, v36
	v_cvt_pk_bf16_f32 v0, v0, s0
	ds_write_b16 v48, v0 offset:54272
	v_mul_f32_e32 v0, v12, v36
	v_cvt_pk_bf16_f32 v0, v0, s0
	v_rcp_f32_e32 v38, v38
	ds_write_b16 v48, v0 offset:54336
	v_mul_f32_e32 v0, v29, v37
	v_cvt_pk_bf16_f32 v0, v0, s0
	ds_write_b16 v48, v0 offset:54400
	v_mul_f32_e32 v0, v13, v37
	v_cvt_pk_bf16_f32 v0, v0, s0
	v_rcp_f32_e32 v39, v39
	ds_write_b16 v48, v0 offset:54464
	v_mul_f32_e32 v0, v30, v38
	v_cvt_pk_bf16_f32 v0, v0, s0
	ds_write_b16 v48, v0 offset:54528
	v_mul_f32_e32 v0, v14, v38
	v_cvt_pk_bf16_f32 v0, v0, s0
	ds_write_b16 v48, v0 offset:54592
	v_mul_f32_e32 v0, v31, v39
	v_cvt_pk_bf16_f32 v0, v0, s0
	ds_write_b16 v48, v0 offset:54656
	v_mul_f32_e32 v0, v15, v39
	s_add_u32 s2, s5, s12
	v_mul_f32_e32 v16, v16, v40
	v_cvt_pk_bf16_f32 v0, v0, s0
	s_addc_u32 s3, s6, 0
	v_cvt_pk_bf16_f32 v16, v16, s0
	ds_write_b16 v48, v0 offset:54720
	s_add_u32 s6, s7, s12
	v_lshlrev_b32_e32 v0, 1, v210
	ds_write_b16 v48, v16 offset:51200
	s_addc_u32 s7, s14, 0
	v_lshrrev_b32_e32 v24, 3, v197
	v_and_b32_e32 v16, 0x70, v0
	v_mov_b32_e32 v17, v193
	v_lshl_add_u64 v[18:19], s[6:7], 0, v[16:17]
	v_lshlrev_b32_e32 v0, 11, v24
	v_mov_b32_e32 v1, v193
	s_waitcnt lgkmcnt(0)
	v_lshl_add_u64 v[0:1], v[18:19], 0, v[0:1]
	global_load_dwordx4 v[0:3], v[0:1], off
	v_or_b32_e32 v25, 8, v24
	v_lshlrev_b32_e32 v4, 11, v25
	v_mov_b32_e32 v5, v193
	v_lshl_add_u64 v[4:5], v[18:19], 0, v[4:5]
	global_load_dwordx4 v[4:7], v[4:5], off
	v_or_b32_e32 v26, 16, v24
	v_lshlrev_b32_e32 v8, 11, v26
	v_mov_b32_e32 v9, v193
	v_lshl_add_u64 v[8:9], v[18:19], 0, v[8:9]
	global_load_dwordx4 v[8:11], v[8:9], off
	v_add_u32_e32 v27, s4, v16
	v_lshl_add_u32 v12, v24, 7, v27
	ds_read_b128 v[12:15], v12 offset:51200
	v_lshl_add_u64 v[20:21], s[2:3], 0, v[16:17]
	v_or_b32_e32 v28, 24, v24
	s_waitcnt lgkmcnt(0)
	v_lshlrev_b32_e32 v16, 16, v12
	v_and_b32_e32 v17, 0xffff0000, v12
	v_lshlrev_b32_e32 v12, 16, v13
	v_and_b32_e32 v13, 0xffff0000, v13
	s_waitcnt vmcnt(2)
	v_lshlrev_b32_e32 v22, 16, v0
	v_and_b32_e32 v23, 0xffff0000, v0
	v_pk_mul_f32 v[16:17], v[16:17], v[22:23]
	v_lshlrev_b32_e32 v22, 16, v2
	v_cvt_pk_bf16_f32 v0, v16, v17
	v_lshlrev_b32_e32 v16, 16, v1
	v_and_b32_e32 v17, 0xffff0000, v1
	v_pk_mul_f32 v[12:13], v[12:13], v[16:17]
	v_lshlrev_b32_e32 v16, 11, v28
	v_mov_b32_e32 v17, v193
	v_lshl_add_u64 v[16:17], v[18:19], 0, v[16:17]
	global_load_dwordx4 v[16:19], v[16:17], off
	v_cvt_pk_bf16_f32 v1, v12, v13
	v_lshlrev_b32_e32 v12, 16, v14
	v_and_b32_e32 v13, 0xffff0000, v14
	v_and_b32_e32 v23, 0xffff0000, v2
	v_pk_mul_f32 v[12:13], v[12:13], v[22:23]
	v_lshlrev_b32_e32 v14, 16, v3
	v_cvt_pk_bf16_f32 v2, v12, v13
	v_lshlrev_b32_e32 v12, 16, v15
	v_and_b32_e32 v13, 0xffff0000, v15
	v_and_b32_e32 v15, 0xffff0000, v3
	v_pk_mul_f32 v[12:13], v[12:13], v[14:15]
	v_lshlrev_b32_e32 v22, 12, v24
	v_cvt_pk_bf16_f32 v3, v12, v13
	v_lshl_add_u32 v12, v25, 7, v27
	ds_read_b128 v[12:15], v12 offset:51200
	v_mov_b32_e32 v23, v193
	v_lshl_add_u64 v[22:23], v[20:21], 0, v[22:23]
	global_store_dwordx4 v[22:23], v[0:3], off
	s_waitcnt lgkmcnt(0)
	s_nop 0
	v_lshlrev_b32_e32 v0, 16, v12
	v_and_b32_e32 v1, 0xffff0000, v12
	s_waitcnt vmcnt(3)
	v_lshlrev_b32_e32 v2, 16, v4
	v_and_b32_e32 v3, 0xffff0000, v4
	v_pk_mul_f32 v[0:1], v[0:1], v[2:3]
	v_lshlrev_b32_e32 v2, 16, v13
	v_and_b32_e32 v3, 0xffff0000, v13
	v_lshlrev_b32_e32 v4, 16, v5
	v_and_b32_e32 v5, 0xffff0000, v5
	v_pk_mul_f32 v[2:3], v[2:3], v[4:5]
	v_cvt_pk_bf16_f32 v0, v0, v1
	v_cvt_pk_bf16_f32 v1, v2, v3
	v_lshlrev_b32_e32 v2, 16, v14
	v_and_b32_e32 v3, 0xffff0000, v14
	v_lshlrev_b32_e32 v4, 16, v6
	v_and_b32_e32 v5, 0xffff0000, v6
	v_pk_mul_f32 v[2:3], v[2:3], v[4:5]
	v_lshlrev_b32_e32 v4, 16, v15
	v_and_b32_e32 v5, 0xffff0000, v15
	v_lshlrev_b32_e32 v6, 16, v7
	v_and_b32_e32 v7, 0xffff0000, v7
	v_pk_mul_f32 v[4:5], v[4:5], v[6:7]
	v_cvt_pk_bf16_f32 v2, v2, v3
	v_cvt_pk_bf16_f32 v3, v4, v5
	v_lshl_add_u32 v4, v26, 7, v27
	ds_read_b128 v[4:7], v4 offset:51200
	v_lshlrev_b32_e32 v12, 12, v25
	v_mov_b32_e32 v13, v193
	v_lshl_add_u64 v[12:13], v[20:21], 0, v[12:13]
	global_store_dwordx4 v[12:13], v[0:3], off
	s_waitcnt lgkmcnt(0)
	s_nop 0
	v_lshlrev_b32_e32 v0, 16, v4
	v_and_b32_e32 v1, 0xffff0000, v4
	s_waitcnt vmcnt(3)
	v_lshlrev_b32_e32 v2, 16, v8
	v_and_b32_e32 v3, 0xffff0000, v8
	v_pk_mul_f32 v[0:1], v[0:1], v[2:3]
	v_lshlrev_b32_e32 v2, 16, v5
	v_and_b32_e32 v3, 0xffff0000, v5
	v_lshlrev_b32_e32 v4, 16, v9
	v_and_b32_e32 v5, 0xffff0000, v9
	v_pk_mul_f32 v[2:3], v[2:3], v[4:5]
	v_cvt_pk_bf16_f32 v0, v0, v1
	v_cvt_pk_bf16_f32 v1, v2, v3
	v_lshlrev_b32_e32 v2, 16, v6
	v_and_b32_e32 v3, 0xffff0000, v6
	v_lshlrev_b32_e32 v4, 16, v10
	v_and_b32_e32 v5, 0xffff0000, v10
	v_pk_mul_f32 v[2:3], v[2:3], v[4:5]
	v_lshlrev_b32_e32 v4, 16, v7
	v_and_b32_e32 v5, 0xffff0000, v7
	v_lshlrev_b32_e32 v6, 16, v11
	v_and_b32_e32 v7, 0xffff0000, v11
	v_pk_mul_f32 v[4:5], v[4:5], v[6:7]
	v_cvt_pk_bf16_f32 v2, v2, v3
	v_cvt_pk_bf16_f32 v3, v4, v5
	v_lshl_add_u32 v4, v28, 7, v27
	ds_read_b128 v[4:7], v4 offset:51200
	v_lshlrev_b32_e32 v8, 12, v26
	v_mov_b32_e32 v9, v193
	v_lshl_add_u64 v[8:9], v[20:21], 0, v[8:9]
	global_store_dwordx4 v[8:9], v[0:3], off
	s_waitcnt lgkmcnt(0)
	s_nop 0
	v_lshlrev_b32_e32 v0, 16, v4
	v_and_b32_e32 v1, 0xffff0000, v4
	s_waitcnt vmcnt(3)
	v_lshlrev_b32_e32 v2, 16, v16
	v_and_b32_e32 v3, 0xffff0000, v16
	v_pk_mul_f32 v[0:1], v[0:1], v[2:3]
	v_lshlrev_b32_e32 v2, 16, v5
	v_and_b32_e32 v3, 0xffff0000, v5
	v_lshlrev_b32_e32 v4, 16, v17
	v_and_b32_e32 v5, 0xffff0000, v17
	v_pk_mul_f32 v[2:3], v[2:3], v[4:5]
	v_cvt_pk_bf16_f32 v0, v0, v1
	v_cvt_pk_bf16_f32 v1, v2, v3
	v_lshlrev_b32_e32 v2, 16, v6
	v_and_b32_e32 v3, 0xffff0000, v6
	v_lshlrev_b32_e32 v4, 16, v18
	v_and_b32_e32 v5, 0xffff0000, v18
	v_pk_mul_f32 v[2:3], v[2:3], v[4:5]
	v_lshlrev_b32_e32 v4, 16, v7
	v_and_b32_e32 v5, 0xffff0000, v7
	v_lshlrev_b32_e32 v6, 16, v19
	v_and_b32_e32 v7, 0xffff0000, v19
	v_pk_mul_f32 v[4:5], v[4:5], v[6:7]
	v_cvt_pk_bf16_f32 v2, v2, v3
	v_cvt_pk_bf16_f32 v3, v4, v5
	v_lshlrev_b32_e32 v4, 12, v28
	v_mov_b32_e32 v5, v193
	v_lshl_add_u64 v[4:5], v[20:21], 0, v[4:5]
	global_store_dwordx4 v[4:5], v[0:3], off
	s_cmp_lg_u32 s13, 0
	s_cbranch_scc1 .Ltk_skip1
	s_waitcnt vmcnt(4)
	v_readfirstlane_b32 s4, v96
	s_nop 3
	s_add_i32 s4, s4, s65
	s_mov_b64 s[6:7], exec
	s_mov_b64 exec, 1
	v_mov_b32_e32 v96, s4
	v_mov_b32_e32 v97, s68
	ds_write_b32 v97, v96
	s_mov_b64 exec, s[6:7]
.Ltk_skip1:
	s_waitcnt lgkmcnt(0)
	s_barrier
	v_mov_b32_e32 v97, s68
	ds_read_b32 v196, v97
	s_waitcnt lgkmcnt(0)
	v_readfirstlane_b32 s20, v196
	s_cmpk_gt_i32 s20, 0x3ff
	s_cbranch_scc1 .LBB0_227
.LBB0_129:
	v_mov_b32_e32 v32, v200
	v_mov_b32_e32 v12, 0
	v_cmp_eq_u32_e32 vcc, 0, v32
	s_and_b32 s18, s20, 63
	s_lshl_b32 s2, s18, 14
	v_readlane_b32 s4, v252, 30
	v_readlane_b32 s5, v252, 31
	s_add_u32 s2, s4, s2
	s_addc_u32 s3, s5, 0
	s_and_b32 s4, s20, 0xffffffc0
	s_sub_i32 s12, 0x400, s4
	v_cmp_gt_i32_e64 s[6:7], s12, v32
	v_mov_b32_e32 v0, 0
	v_mov_b32_e32 v4, 0
	v_mov_b32_e32 v5, 0
	v_mov_b32_e32 v6, 0
	v_mov_b32_e32 v7, 0
	s_and_saveexec_b64 s[4:5], s[6:7]
	s_cbranch_execz .LBB0_135
	v_ashrrev_i32_e32 v33, 31, v32
	v_lshl_add_u64 v[2:3], v[32:33], 4, s[2:3]
	global_load_dwordx4 v[4:7], v[2:3], off

.LBB0_141:
.LBB0_142:
	s_or_b64 exec, exec, s[2:3]
	s_lshl_b32 s6, s19, 2
	s_add_i32 s2, s6, 4
	v_cmp_gt_u32_e32 vcc, s2, v244
	s_mov_b64 s[2:3], 0
	s_waitcnt lgkmcnt(0)
	s_barrier
	s_and_saveexec_b64 s[4:5], vcc
	s_cbranch_execz .LBB0_144
	v_readlane_b32 s2, v253, 33
	s_nop 1
	v_mov_b32_e32 v0, s2
	ds_read_b128 v[0:3], v0
	v_readlane_b32 s2, v253, 34
	s_waitcnt lgkmcnt(0)
	v_max_f32_e32 v1, v1, v1
	v_max_f32_e32 v0, v0, v0
	v_max_f32_e32 v0, v0, v1
	v_max3_f32 v4, v0, v2, v3
	v_mov_b32_e32 v0, s2
	ds_read_b128 v[0:3], v0
	s_lshl_b32 s2, s18, 3
	s_waitcnt lgkmcnt(0)
	v_max3_f32 v0, v4, v0, v1
	v_max3_f32 v2, v0, v2, v3
	v_add_f32_e32 v0, v34, v35
	v_mul_f32_e32 v0, v2, v0
	v_cmp_gt_f32_e32 vcc, s61, v0
	v_mul_f32_e32 v1, 0x4f800000, v0
	s_nop 0
	v_cndmask_b32_e32 v0, v0, v1, vcc
	v_sqrt_f32_e32 v1, v0
	s_nop 0
	v_add_u32_e32 v2, -1, v1
	v_fma_f32 v3, -v2, v1, v0
	v_cmp_ge_f32_e64 s[2:3], 0, v3
	v_add_u32_e32 v3, 1, v1
	s_nop 0
	v_cndmask_b32_e64 v2, v1, v2, s[2:3]
	v_fma_f32 v1, -v3, v1, v0
	v_cmp_lt_f32_e64 s[2:3], 0, v1
	s_nop 1
	v_cndmask_b32_e64 v1, v2, v3, s[2:3]
	v_mul_f32_e32 v2, 0x37800000, v1
	v_cndmask_b32_e32 v1, v1, v2, vcc
	v_cmp_class_f32_e32 vcc, v0, v226
	s_lshl_b32 s2, s14, 2
	s_add_i32 s3, 0, 0x14800
	v_cndmask_b32_e32 v0, v1, v0, vcc
	s_add_i32 s2, s3, s2
	v_add_f32_e32 v0, v0, v0
	v_mov_b32_e32 v2, 0x42800000
	v_mov_b32_e32 v1, s2
	v_fmamk_f32 v0, v0, 0x3f8020c5, v2
	v_add_u32_e32 v2, s3, v201
	ds_read_b32 v1, v1
	ds_read_b32 v2, v2 offset:252
	s_waitcnt lgkmcnt(0)
	v_sub_f32_e32 v1, v1, v2
	v_cmp_gt_f32_e32 vcc, v1, v0
	s_and_b64 s[2:3], vcc, exec
